# stack + FFN-down fused epilogue: per-row (mean,rstd) pairs read from LDS once instead of in each of 32 blocks
# speedup vs baseline: 1.0136x; 1.0071x over previous
.LBB0_382:
	v_lshl_add_u32 v0, v196, 3, 0
	ds_read_b64 v[220:221], v0 offset:8192
	ds_read_b64 v[222:223], v0 offset:8320
	ds_read_b64 v[224:225], v0 offset:8448
	ds_read_b64 v[226:227], v0 offset:8576
	ds_read_b64 v[228:229], v0 offset:9216
	ds_read_b64 v[230:231], v0 offset:9344
	ds_read_b64 v[232:233], v0 offset:9472
	ds_read_b64 v[234:235], v0 offset:9600
	s_waitcnt lgkmcnt(0)
	v_mov_b64_e32 v[206:207], v[220:221]
	s_lshl_b64 s[8:9], s[24:25], 12
	s_add_u32 s20, s20, s8
	s_addc_u32 s21, s21, s9
	s_sub_u32 s2, 0, s26
	s_subb_u32 s8, 0, s27
	s_waitcnt lgkmcnt(0)
	v_sub_f32_e32 v143, v143, v206
	v_sub_f32_e32 v142, v142, v206
	v_sub_f32_e32 v145, v145, v206
	v_sub_f32_e32 v144, v144, v206
	s_add_u32 s10, s20, s2
	v_lshlrev_b64 v[196:197], 10, v[196:197]
	v_pk_mul_f32 v[144:145], v[206:207], v[144:145] op_sel:[1,0]
	v_pk_mul_f32 v[142:143], v[206:207], v[142:143] op_sel:[1,0]
	s_addc_u32 s11, s21, s8
	v_lshl_add_u64 v[196:197], v[196:197], 0, v[180:181]
	s_waitcnt vmcnt(0)
	v_pk_fma_f32 v[142:143], v[158:159], v[142:143], v[162:163]
	v_pk_fma_f32 v[144:145], v[160:161], v[144:145], v[164:165]
	v_cmp_eq_u32_e64 s[8:9], 0, v208
	s_mov_b64 s[22:23], -1
	s_and_b64 vcc, exec, s[4:5]
	v_cndmask_b32_e64 v145, v250, v145, s[8:9]
	v_cndmask_b32_e64 v144, v250, v144, s[8:9]
	v_cndmask_b32_e64 v143, v250, v143, s[8:9]
	v_cndmask_b32_e64 v142, v250, v142, s[8:9]
	v_lshl_add_u64 v[208:209], v[196:197], 2, s[20:21]
	s_cbranch_vccnz .LBB0_384
	s_mov_b64 s[22:23], 0
	global_store_dwordx4 v[208:209], v[142:145], off

.LBB0_388:
	v_mov_b64_e32 v[144:145], v[222:223]
	v_lshlrev_b64 v[142:143], 10, v[194:195]
	v_lshl_add_u64 v[142:143], v[142:143], 0, v[180:181]
	s_mov_b64 s[22:23], -1
	s_and_b64 vcc, exec, s[4:5]
	s_waitcnt lgkmcnt(0)
	v_sub_f32_e32 v139, v139, v144
	v_sub_f32_e32 v138, v138, v144
	v_sub_f32_e32 v141, v141, v144
	v_sub_f32_e32 v140, v140, v144
	v_pk_mul_f32 v[140:141], v[144:145], v[140:141] op_sel:[1,0]
	v_pk_mul_f32 v[138:139], v[144:145], v[138:139] op_sel:[1,0]
	v_pk_fma_f32 v[140:141], v[160:161], v[140:141], v[164:165]
	v_pk_fma_f32 v[138:139], v[158:159], v[138:139], v[162:163]
	v_cndmask_b32_e64 v141, v250, v141, s[8:9]
	v_cndmask_b32_e64 v140, v250, v140, s[8:9]
	v_cndmask_b32_e64 v139, v250, v139, s[8:9]
	v_cndmask_b32_e64 v138, v250, v138, s[8:9]
	v_lshl_add_u64 v[194:195], v[142:143], 2, s[20:21]
	s_cbranch_vccz .LBB0_528
	s_andn2_b64 vcc, exec, s[22:23]
	v_lshl_add_u64 v[144:145], v[142:143], 1, s[10:11]
	s_cbranch_vccz .LBB0_529

.LBB0_392:
	v_mov_b64_e32 v[140:141], v[224:225]
	v_lshlrev_b64 v[138:139], 10, v[192:193]
	v_lshl_add_u64 v[138:139], v[138:139], 0, v[180:181]
	s_mov_b64 s[22:23], -1
	s_and_b64 vcc, exec, s[4:5]
	s_waitcnt lgkmcnt(0)
	v_sub_f32_e32 v135, v135, v140
	v_sub_f32_e32 v134, v134, v140
	v_sub_f32_e32 v137, v137, v140
	v_sub_f32_e32 v136, v136, v140
	v_pk_mul_f32 v[136:137], v[140:141], v[136:137] op_sel:[1,0]
	v_pk_mul_f32 v[134:135], v[140:141], v[134:135] op_sel:[1,0]
	v_pk_fma_f32 v[136:137], v[160:161], v[136:137], v[164:165]
	v_pk_fma_f32 v[134:135], v[158:159], v[134:135], v[162:163]
	v_cndmask_b32_e64 v137, v250, v137, s[8:9]
	v_cndmask_b32_e64 v136, v250, v136, s[8:9]
	v_cndmask_b32_e64 v135, v250, v135, s[8:9]
	v_cndmask_b32_e64 v134, v250, v134, s[8:9]
	v_lshl_add_u64 v[192:193], v[138:139], 2, s[20:21]
	s_cbranch_vccz .LBB0_530
	s_andn2_b64 vcc, exec, s[22:23]
	v_lshl_add_u64 v[140:141], v[138:139], 1, s[10:11]
	s_cbranch_vccz .LBB0_531

.LBB0_396:
	v_mov_b64_e32 v[136:137], v[226:227]
	v_lshlrev_b64 v[134:135], 10, v[190:191]
	v_lshl_add_u64 v[134:135], v[134:135], 0, v[180:181]
	s_mov_b64 s[22:23], -1
	s_and_b64 vcc, exec, s[4:5]
	s_waitcnt lgkmcnt(0)
	v_sub_f32_e32 v131, v131, v136
	v_sub_f32_e32 v130, v130, v136
	v_sub_f32_e32 v133, v133, v136
	v_sub_f32_e32 v132, v132, v136
	v_pk_mul_f32 v[132:133], v[136:137], v[132:133] op_sel:[1,0]
	v_pk_mul_f32 v[130:131], v[136:137], v[130:131] op_sel:[1,0]
	v_pk_fma_f32 v[132:133], v[160:161], v[132:133], v[164:165]
	v_pk_fma_f32 v[130:131], v[158:159], v[130:131], v[162:163]
	v_cndmask_b32_e64 v133, v250, v133, s[8:9]
	v_cndmask_b32_e64 v132, v250, v132, s[8:9]
	v_cndmask_b32_e64 v131, v250, v131, s[8:9]
	v_cndmask_b32_e64 v130, v250, v130, s[8:9]
	v_lshl_add_u64 v[190:191], v[134:135], 2, s[20:21]
	s_cbranch_vccz .LBB0_532
	s_andn2_b64 vcc, exec, s[22:23]
	v_lshl_add_u64 v[136:137], v[134:135], 1, s[10:11]
	s_cbranch_vccz .LBB0_533

.LBB0_400:
	v_mov_b64_e32 v[132:133], v[228:229]
	v_lshlrev_b64 v[130:131], 10, v[188:189]
	v_lshl_add_u64 v[130:131], v[130:131], 0, v[180:181]
	s_mov_b64 s[22:23], -1
	s_and_b64 vcc, exec, s[4:5]
	s_waitcnt lgkmcnt(0)
	v_sub_f32_e32 v127, v127, v132
	v_sub_f32_e32 v126, v126, v132
	v_sub_f32_e32 v129, v129, v132
	v_sub_f32_e32 v128, v128, v132
	v_pk_mul_f32 v[128:129], v[132:133], v[128:129] op_sel:[1,0]
	v_pk_mul_f32 v[126:127], v[132:133], v[126:127] op_sel:[1,0]
	v_pk_fma_f32 v[128:129], v[160:161], v[128:129], v[164:165]
	v_pk_fma_f32 v[126:127], v[158:159], v[126:127], v[162:163]
	v_cndmask_b32_e64 v129, v250, v129, s[8:9]
	v_cndmask_b32_e64 v128, v250, v128, s[8:9]
	v_cndmask_b32_e64 v127, v250, v127, s[8:9]
	v_cndmask_b32_e64 v126, v250, v126, s[8:9]
	v_lshl_add_u64 v[188:189], v[130:131], 2, s[20:21]
	s_cbranch_vccz .LBB0_534
	s_andn2_b64 vcc, exec, s[22:23]
	v_lshl_add_u64 v[132:133], v[130:131], 1, s[10:11]
	s_cbranch_vccz .LBB0_535

.LBB0_404:
	v_mov_b64_e32 v[128:129], v[230:231]
	v_lshlrev_b64 v[126:127], 10, v[186:187]
	v_lshl_add_u64 v[126:127], v[126:127], 0, v[180:181]
	s_mov_b64 s[22:23], -1
	s_and_b64 vcc, exec, s[4:5]
	s_waitcnt lgkmcnt(0)
	v_sub_f32_e32 v123, v123, v128
	v_sub_f32_e32 v122, v122, v128
	v_sub_f32_e32 v125, v125, v128
	v_sub_f32_e32 v124, v124, v128
	v_pk_mul_f32 v[124:125], v[128:129], v[124:125] op_sel:[1,0]
	v_pk_mul_f32 v[122:123], v[128:129], v[122:123] op_sel:[1,0]
	v_pk_fma_f32 v[124:125], v[160:161], v[124:125], v[164:165]
	v_pk_fma_f32 v[122:123], v[158:159], v[122:123], v[162:163]
	v_cndmask_b32_e64 v125, v250, v125, s[8:9]
	v_cndmask_b32_e64 v124, v250, v124, s[8:9]
	v_cndmask_b32_e64 v123, v250, v123, s[8:9]
	v_cndmask_b32_e64 v122, v250, v122, s[8:9]
	v_lshl_add_u64 v[186:187], v[126:127], 2, s[20:21]
	s_cbranch_vccz .LBB0_536
	s_andn2_b64 vcc, exec, s[22:23]
	v_lshl_add_u64 v[128:129], v[126:127], 1, s[10:11]
	s_cbranch_vccz .LBB0_537

.LBB0_408:
	v_mov_b64_e32 v[124:125], v[232:233]
	v_lshlrev_b64 v[122:123], 10, v[184:185]
	v_lshl_add_u64 v[122:123], v[122:123], 0, v[180:181]
	s_mov_b64 s[22:23], -1
	s_and_b64 vcc, exec, s[4:5]
	s_waitcnt lgkmcnt(0)
	v_sub_f32_e32 v119, v119, v124
	v_sub_f32_e32 v118, v118, v124
	v_sub_f32_e32 v121, v121, v124
	v_sub_f32_e32 v120, v120, v124
	v_pk_mul_f32 v[120:121], v[124:125], v[120:121] op_sel:[1,0]
	v_pk_mul_f32 v[118:119], v[124:125], v[118:119] op_sel:[1,0]
	v_pk_fma_f32 v[120:121], v[160:161], v[120:121], v[164:165]
	v_pk_fma_f32 v[118:119], v[158:159], v[118:119], v[162:163]
	v_cndmask_b32_e64 v121, v250, v121, s[8:9]
	v_cndmask_b32_e64 v120, v250, v120, s[8:9]
	v_cndmask_b32_e64 v119, v250, v119, s[8:9]
	v_cndmask_b32_e64 v118, v250, v118, s[8:9]
	v_lshl_add_u64 v[184:185], v[122:123], 2, s[20:21]
	s_cbranch_vccz .LBB0_538
	s_andn2_b64 vcc, exec, s[22:23]
	v_lshl_add_u64 v[124:125], v[122:123], 1, s[10:11]
	s_cbranch_vccz .LBB0_539

.LBB0_412:
	v_mov_b64_e32 v[120:121], v[234:235]
	v_lshlrev_b64 v[118:119], 10, v[182:183]
	v_lshl_add_u64 v[118:119], v[118:119], 0, v[180:181]
	s_mov_b64 s[22:23], -1
	s_and_b64 vcc, exec, s[4:5]
	s_waitcnt lgkmcnt(0)
	v_sub_f32_e32 v115, v115, v120
	v_sub_f32_e32 v114, v114, v120
	v_sub_f32_e32 v117, v117, v120
	v_sub_f32_e32 v116, v116, v120
	v_pk_mul_f32 v[116:117], v[120:121], v[116:117] op_sel:[1,0]
	v_pk_mul_f32 v[114:115], v[120:121], v[114:115] op_sel:[1,0]
	v_pk_fma_f32 v[116:117], v[160:161], v[116:117], v[164:165]
	v_pk_fma_f32 v[114:115], v[158:159], v[114:115], v[162:163]
	v_cndmask_b32_e64 v117, v250, v117, s[8:9]
	v_cndmask_b32_e64 v116, v250, v116, s[8:9]
	v_cndmask_b32_e64 v115, v250, v115, s[8:9]
	v_cndmask_b32_e64 v114, v250, v114, s[8:9]
	v_lshl_add_u64 v[158:159], v[118:119], 2, s[20:21]
	s_cbranch_vccz .LBB0_540
	s_andn2_b64 vcc, exec, s[22:23]
	v_lshl_add_u64 v[120:121], v[118:119], 1, s[10:11]
	s_cbranch_vccz .LBB0_541

.LBB0_416:
	v_mov_b64_e32 v[114:115], v[220:221]
	s_and_b64 vcc, exec, s[4:5]
	s_mov_b64 s[10:11], -1
	s_waitcnt lgkmcnt(0)
	v_sub_f32_e32 v111, v111, v114
	v_sub_f32_e32 v110, v110, v114
	v_sub_f32_e32 v113, v113, v114
	v_sub_f32_e32 v112, v112, v114
	v_pk_mul_f32 v[112:113], v[114:115], v[112:113] op_sel:[1,0]
	v_pk_mul_f32 v[110:111], v[114:115], v[110:111] op_sel:[1,0]
	v_pk_fma_f32 v[112:113], v[148:149], v[112:113], v[152:153]
	v_pk_fma_f32 v[110:111], v[146:147], v[110:111], v[150:151]
	v_cndmask_b32_e64 v113, v250, v113, s[8:9]
	v_cndmask_b32_e64 v112, v250, v112, s[8:9]
	v_cndmask_b32_e64 v111, v250, v111, s[8:9]
	v_cndmask_b32_e64 v110, v250, v110, s[8:9]
	s_cbranch_vccz .LBB0_542
	s_andn2_b64 vcc, exec, s[10:11]
	s_cbranch_vccz .LBB0_543

.LBB0_420:
	v_mov_b64_e32 v[110:111], v[222:223]
	s_and_b64 vcc, exec, s[4:5]
	s_mov_b64 s[10:11], -1
	s_waitcnt lgkmcnt(0)
	v_sub_f32_e32 v107, v107, v110
	v_sub_f32_e32 v106, v106, v110
	v_sub_f32_e32 v109, v109, v110
	v_sub_f32_e32 v108, v108, v110
	v_pk_mul_f32 v[108:109], v[110:111], v[108:109] op_sel:[1,0]
	v_pk_mul_f32 v[106:107], v[110:111], v[106:107] op_sel:[1,0]
	v_pk_fma_f32 v[108:109], v[148:149], v[108:109], v[152:153]
	v_pk_fma_f32 v[106:107], v[146:147], v[106:107], v[150:151]
	v_cndmask_b32_e64 v109, v250, v109, s[8:9]
	v_cndmask_b32_e64 v108, v250, v108, s[8:9]
	v_cndmask_b32_e64 v107, v250, v107, s[8:9]
	v_cndmask_b32_e64 v106, v250, v106, s[8:9]
	s_cbranch_vccz .LBB0_544
	s_andn2_b64 vcc, exec, s[10:11]
	s_cbranch_vccz .LBB0_545

.LBB0_424:
	v_mov_b64_e32 v[106:107], v[224:225]
	s_and_b64 vcc, exec, s[4:5]
	s_mov_b64 s[10:11], -1
	s_waitcnt lgkmcnt(0)
	v_sub_f32_e32 v103, v103, v106
	v_sub_f32_e32 v102, v102, v106
	v_sub_f32_e32 v105, v105, v106
	v_sub_f32_e32 v104, v104, v106
	v_pk_mul_f32 v[104:105], v[106:107], v[104:105] op_sel:[1,0]
	v_pk_mul_f32 v[102:103], v[106:107], v[102:103] op_sel:[1,0]
	v_pk_fma_f32 v[104:105], v[148:149], v[104:105], v[152:153]
	v_pk_fma_f32 v[102:103], v[146:147], v[102:103], v[150:151]
	v_cndmask_b32_e64 v105, v250, v105, s[8:9]
	v_cndmask_b32_e64 v104, v250, v104, s[8:9]
	v_cndmask_b32_e64 v103, v250, v103, s[8:9]
	v_cndmask_b32_e64 v102, v250, v102, s[8:9]
	s_cbranch_vccz .LBB0_546
	s_andn2_b64 vcc, exec, s[10:11]
	s_cbranch_vccz .LBB0_547

.LBB0_428:
	v_mov_b64_e32 v[102:103], v[226:227]
	s_and_b64 vcc, exec, s[4:5]
	s_mov_b64 s[10:11], -1
	s_waitcnt lgkmcnt(0)
	v_sub_f32_e32 v99, v99, v102
	v_sub_f32_e32 v98, v98, v102
	v_sub_f32_e32 v101, v101, v102
	v_sub_f32_e32 v100, v100, v102
	v_pk_mul_f32 v[100:101], v[102:103], v[100:101] op_sel:[1,0]
	v_pk_mul_f32 v[98:99], v[102:103], v[98:99] op_sel:[1,0]
	v_pk_fma_f32 v[100:101], v[148:149], v[100:101], v[152:153]
	v_pk_fma_f32 v[98:99], v[146:147], v[98:99], v[150:151]
	v_cndmask_b32_e64 v101, v250, v101, s[8:9]
	v_cndmask_b32_e64 v100, v250, v100, s[8:9]
	v_cndmask_b32_e64 v99, v250, v99, s[8:9]
	v_cndmask_b32_e64 v98, v250, v98, s[8:9]
	s_cbranch_vccz .LBB0_548
	s_andn2_b64 vcc, exec, s[10:11]
	s_cbranch_vccz .LBB0_549

.LBB0_432:
	v_mov_b64_e32 v[98:99], v[228:229]
	s_and_b64 vcc, exec, s[4:5]
	s_mov_b64 s[10:11], -1
	s_waitcnt lgkmcnt(0)
	v_sub_f32_e32 v95, v95, v98
	v_sub_f32_e32 v94, v94, v98
	v_sub_f32_e32 v97, v97, v98
	v_sub_f32_e32 v96, v96, v98
	v_pk_mul_f32 v[96:97], v[98:99], v[96:97] op_sel:[1,0]
	v_pk_mul_f32 v[94:95], v[98:99], v[94:95] op_sel:[1,0]
	v_pk_fma_f32 v[96:97], v[148:149], v[96:97], v[152:153]
	v_pk_fma_f32 v[94:95], v[146:147], v[94:95], v[150:151]
	v_cndmask_b32_e64 v97, v250, v97, s[8:9]
	v_cndmask_b32_e64 v96, v250, v96, s[8:9]
	v_cndmask_b32_e64 v95, v250, v95, s[8:9]
	v_cndmask_b32_e64 v94, v250, v94, s[8:9]
	s_cbranch_vccz .LBB0_550
	s_andn2_b64 vcc, exec, s[10:11]
	s_cbranch_vccz .LBB0_551

.LBB0_436:
	v_mov_b64_e32 v[94:95], v[230:231]
	s_and_b64 vcc, exec, s[4:5]
	s_mov_b64 s[10:11], -1
	s_waitcnt lgkmcnt(0)
	v_sub_f32_e32 v91, v91, v94
	v_sub_f32_e32 v90, v90, v94
	v_sub_f32_e32 v93, v93, v94
	v_sub_f32_e32 v92, v92, v94
	v_pk_mul_f32 v[92:93], v[94:95], v[92:93] op_sel:[1,0]
	v_pk_mul_f32 v[90:91], v[94:95], v[90:91] op_sel:[1,0]
	v_pk_fma_f32 v[92:93], v[148:149], v[92:93], v[152:153]
	v_pk_fma_f32 v[90:91], v[146:147], v[90:91], v[150:151]
	v_cndmask_b32_e64 v93, v250, v93, s[8:9]
	v_cndmask_b32_e64 v92, v250, v92, s[8:9]
	v_cndmask_b32_e64 v91, v250, v91, s[8:9]
	v_cndmask_b32_e64 v90, v250, v90, s[8:9]
	s_cbranch_vccz .LBB0_552
	s_andn2_b64 vcc, exec, s[10:11]
	s_cbranch_vccz .LBB0_553

.LBB0_440:
	v_mov_b64_e32 v[90:91], v[232:233]
	s_and_b64 vcc, exec, s[4:5]
	s_mov_b64 s[10:11], -1
	s_waitcnt lgkmcnt(0)
	v_sub_f32_e32 v79, v79, v90
	v_sub_f32_e32 v78, v78, v90
	v_sub_f32_e32 v81, v81, v90
	v_sub_f32_e32 v80, v80, v90
	v_pk_mul_f32 v[80:81], v[90:91], v[80:81] op_sel:[1,0]
	v_pk_mul_f32 v[78:79], v[90:91], v[78:79] op_sel:[1,0]
	v_pk_fma_f32 v[80:81], v[148:149], v[80:81], v[152:153]
	v_pk_fma_f32 v[78:79], v[146:147], v[78:79], v[150:151]
	v_cndmask_b32_e64 v81, v250, v81, s[8:9]
	v_cndmask_b32_e64 v80, v250, v80, s[8:9]
	v_cndmask_b32_e64 v79, v250, v79, s[8:9]
	v_cndmask_b32_e64 v78, v250, v78, s[8:9]
	s_cbranch_vccz .LBB0_554
	s_andn2_b64 vcc, exec, s[10:11]
	s_cbranch_vccz .LBB0_555

.LBB0_444:
	v_mov_b64_e32 v[78:79], v[234:235]
	s_and_b64 vcc, exec, s[4:5]
	s_mov_b64 s[10:11], -1
	s_waitcnt lgkmcnt(0)
	v_sub_f32_e32 v75, v75, v78
	v_sub_f32_e32 v74, v74, v78
	v_sub_f32_e32 v77, v77, v78
	v_sub_f32_e32 v76, v76, v78
	v_pk_mul_f32 v[76:77], v[78:79], v[76:77] op_sel:[1,0]
	v_pk_mul_f32 v[74:75], v[78:79], v[74:75] op_sel:[1,0]
	v_pk_fma_f32 v[76:77], v[148:149], v[76:77], v[152:153]
	v_pk_fma_f32 v[74:75], v[146:147], v[74:75], v[150:151]
	v_cndmask_b32_e64 v77, v250, v77, s[8:9]
	v_cndmask_b32_e64 v76, v250, v76, s[8:9]
	v_cndmask_b32_e64 v75, v250, v75, s[8:9]
	v_cndmask_b32_e64 v74, v250, v74, s[8:9]
	s_cbranch_vccz .LBB0_556
	s_andn2_b64 vcc, exec, s[10:11]
	s_cbranch_vccz .LBB0_557

.LBB0_448:
	v_mov_b64_e32 v[74:75], v[220:221]
	s_and_b64 vcc, exec, s[4:5]
	s_mov_b64 s[10:11], -1
	s_waitcnt lgkmcnt(0)
	v_sub_f32_e32 v71, v71, v74
	v_sub_f32_e32 v70, v70, v74
	v_sub_f32_e32 v73, v73, v74
	v_sub_f32_e32 v72, v72, v74
	v_pk_mul_f32 v[72:73], v[74:75], v[72:73] op_sel:[1,0]
	v_pk_mul_f32 v[70:71], v[74:75], v[70:71] op_sel:[1,0]
	v_pk_fma_f32 v[72:73], v[84:85], v[72:73], v[88:89]
	v_pk_fma_f32 v[70:71], v[82:83], v[70:71], v[86:87]
	v_cndmask_b32_e64 v73, v250, v73, s[8:9]
	v_cndmask_b32_e64 v72, v250, v72, s[8:9]
	v_cndmask_b32_e64 v71, v250, v71, s[8:9]
	v_cndmask_b32_e64 v70, v250, v70, s[8:9]
	s_cbranch_vccz .LBB0_558
	s_andn2_b64 vcc, exec, s[10:11]
	s_cbranch_vccz .LBB0_559

.LBB0_452:
	v_mov_b64_e32 v[70:71], v[222:223]
	s_and_b64 vcc, exec, s[4:5]
	s_mov_b64 s[10:11], -1
	s_waitcnt lgkmcnt(0)
	v_sub_f32_e32 v67, v67, v70
	v_sub_f32_e32 v66, v66, v70
	v_sub_f32_e32 v69, v69, v70
	v_sub_f32_e32 v68, v68, v70
	v_pk_mul_f32 v[68:69], v[70:71], v[68:69] op_sel:[1,0]
	v_pk_mul_f32 v[66:67], v[70:71], v[66:67] op_sel:[1,0]
	v_pk_fma_f32 v[68:69], v[84:85], v[68:69], v[88:89]
	v_pk_fma_f32 v[66:67], v[82:83], v[66:67], v[86:87]
	v_cndmask_b32_e64 v69, v250, v69, s[8:9]
	v_cndmask_b32_e64 v68, v250, v68, s[8:9]
	v_cndmask_b32_e64 v67, v250, v67, s[8:9]
	v_cndmask_b32_e64 v66, v250, v66, s[8:9]
	s_cbranch_vccz .LBB0_560
	s_andn2_b64 vcc, exec, s[10:11]
	s_cbranch_vccz .LBB0_561

.LBB0_456:
	v_mov_b64_e32 v[66:67], v[224:225]
	s_and_b64 vcc, exec, s[4:5]
	s_mov_b64 s[10:11], -1
	s_waitcnt lgkmcnt(0)
	v_sub_f32_e32 v63, v63, v66
	v_sub_f32_e32 v62, v62, v66
	v_sub_f32_e32 v65, v65, v66
	v_sub_f32_e32 v64, v64, v66
	v_pk_mul_f32 v[64:65], v[66:67], v[64:65] op_sel:[1,0]
	v_pk_mul_f32 v[62:63], v[66:67], v[62:63] op_sel:[1,0]
	v_pk_fma_f32 v[64:65], v[84:85], v[64:65], v[88:89]
	v_pk_fma_f32 v[62:63], v[82:83], v[62:63], v[86:87]
	v_cndmask_b32_e64 v65, v250, v65, s[8:9]
	v_cndmask_b32_e64 v64, v250, v64, s[8:9]
	v_cndmask_b32_e64 v63, v250, v63, s[8:9]
	v_cndmask_b32_e64 v62, v250, v62, s[8:9]
	s_cbranch_vccz .LBB0_562
	s_andn2_b64 vcc, exec, s[10:11]
	s_cbranch_vccz .LBB0_563

.LBB0_460:
	v_mov_b64_e32 v[62:63], v[226:227]
	s_and_b64 vcc, exec, s[4:5]
	s_mov_b64 s[10:11], -1
	s_waitcnt lgkmcnt(0)
	v_sub_f32_e32 v59, v59, v62
	v_sub_f32_e32 v58, v58, v62
	v_sub_f32_e32 v61, v61, v62
	v_sub_f32_e32 v60, v60, v62
	v_pk_mul_f32 v[60:61], v[62:63], v[60:61] op_sel:[1,0]
	v_pk_mul_f32 v[58:59], v[62:63], v[58:59] op_sel:[1,0]
	v_pk_fma_f32 v[60:61], v[84:85], v[60:61], v[88:89]
	v_pk_fma_f32 v[58:59], v[82:83], v[58:59], v[86:87]
	v_cndmask_b32_e64 v61, v250, v61, s[8:9]
	v_cndmask_b32_e64 v60, v250, v60, s[8:9]
	v_cndmask_b32_e64 v59, v250, v59, s[8:9]
	v_cndmask_b32_e64 v58, v250, v58, s[8:9]
	s_cbranch_vccz .LBB0_564
	s_andn2_b64 vcc, exec, s[10:11]
	s_cbranch_vccz .LBB0_565

.LBB0_464:
	v_mov_b64_e32 v[58:59], v[228:229]
	s_and_b64 vcc, exec, s[4:5]
	s_mov_b64 s[10:11], -1
	s_waitcnt lgkmcnt(0)
	v_sub_f32_e32 v55, v55, v58
	v_sub_f32_e32 v54, v54, v58
	v_sub_f32_e32 v57, v57, v58
	v_sub_f32_e32 v56, v56, v58
	v_pk_mul_f32 v[56:57], v[58:59], v[56:57] op_sel:[1,0]
	v_pk_mul_f32 v[54:55], v[58:59], v[54:55] op_sel:[1,0]
	v_pk_fma_f32 v[56:57], v[84:85], v[56:57], v[88:89]
	v_pk_fma_f32 v[54:55], v[82:83], v[54:55], v[86:87]
	v_cndmask_b32_e64 v57, v250, v57, s[8:9]
	v_cndmask_b32_e64 v56, v250, v56, s[8:9]
	v_cndmask_b32_e64 v55, v250, v55, s[8:9]
	v_cndmask_b32_e64 v54, v250, v54, s[8:9]
	s_cbranch_vccz .LBB0_566
	s_andn2_b64 vcc, exec, s[10:11]
	s_cbranch_vccz .LBB0_567

.LBB0_468:
	v_mov_b64_e32 v[54:55], v[230:231]
	s_and_b64 vcc, exec, s[4:5]
	s_mov_b64 s[10:11], -1
	s_waitcnt lgkmcnt(0)
	v_sub_f32_e32 v51, v51, v54
	v_sub_f32_e32 v50, v50, v54
	v_sub_f32_e32 v53, v53, v54
	v_sub_f32_e32 v52, v52, v54
	v_pk_mul_f32 v[52:53], v[54:55], v[52:53] op_sel:[1,0]
	v_pk_mul_f32 v[50:51], v[54:55], v[50:51] op_sel:[1,0]
	v_pk_fma_f32 v[52:53], v[84:85], v[52:53], v[88:89]
	v_pk_fma_f32 v[50:51], v[82:83], v[50:51], v[86:87]
	v_cndmask_b32_e64 v53, v250, v53, s[8:9]
	v_cndmask_b32_e64 v52, v250, v52, s[8:9]
	v_cndmask_b32_e64 v51, v250, v51, s[8:9]
	v_cndmask_b32_e64 v50, v250, v50, s[8:9]
	s_cbranch_vccz .LBB0_568
	s_andn2_b64 vcc, exec, s[10:11]
	s_cbranch_vccz .LBB0_569

.LBB0_472:
	v_mov_b64_e32 v[50:51], v[232:233]
	s_and_b64 vcc, exec, s[4:5]
	s_mov_b64 s[10:11], -1
	s_waitcnt lgkmcnt(0)
	v_sub_f32_e32 v47, v47, v50
	v_sub_f32_e32 v46, v46, v50
	v_sub_f32_e32 v49, v49, v50
	v_sub_f32_e32 v48, v48, v50
	v_pk_mul_f32 v[48:49], v[50:51], v[48:49] op_sel:[1,0]
	v_pk_mul_f32 v[46:47], v[50:51], v[46:47] op_sel:[1,0]
	v_pk_fma_f32 v[48:49], v[84:85], v[48:49], v[88:89]
	v_pk_fma_f32 v[46:47], v[82:83], v[46:47], v[86:87]
	v_cndmask_b32_e64 v49, v250, v49, s[8:9]
	v_cndmask_b32_e64 v48, v250, v48, s[8:9]
	v_cndmask_b32_e64 v47, v250, v47, s[8:9]
	v_cndmask_b32_e64 v46, v250, v46, s[8:9]
	s_cbranch_vccz .LBB0_570
	s_andn2_b64 vcc, exec, s[10:11]
	s_cbranch_vccz .LBB0_571

.LBB0_476:
	v_mov_b64_e32 v[46:47], v[234:235]
	s_and_b64 vcc, exec, s[4:5]
	s_mov_b64 s[10:11], -1
	s_waitcnt lgkmcnt(0)
	v_sub_f32_e32 v43, v43, v46
	v_sub_f32_e32 v42, v42, v46
	v_sub_f32_e32 v45, v45, v46
	v_sub_f32_e32 v44, v44, v46
	v_pk_mul_f32 v[44:45], v[46:47], v[44:45] op_sel:[1,0]
	v_pk_mul_f32 v[42:43], v[46:47], v[42:43] op_sel:[1,0]
	v_pk_fma_f32 v[44:45], v[84:85], v[44:45], v[88:89]
	v_pk_fma_f32 v[42:43], v[82:83], v[42:43], v[86:87]
	v_cndmask_b32_e64 v45, v250, v45, s[8:9]
	v_cndmask_b32_e64 v44, v250, v44, s[8:9]
	v_cndmask_b32_e64 v43, v250, v43, s[8:9]
	v_cndmask_b32_e64 v42, v250, v42, s[8:9]
	s_cbranch_vccz .LBB0_572
	s_andn2_b64 vcc, exec, s[10:11]
	s_cbranch_vccz .LBB0_573

.LBB0_480:
	v_mov_b64_e32 v[42:43], v[220:221]
	s_and_b64 vcc, exec, s[4:5]
	s_mov_b64 s[10:11], -1
	s_waitcnt lgkmcnt(0)
	v_sub_f32_e32 v39, v39, v42
	v_sub_f32_e32 v38, v38, v42
	v_sub_f32_e32 v41, v41, v42
	v_sub_f32_e32 v40, v40, v42
	v_pk_mul_f32 v[40:41], v[42:43], v[40:41] op_sel:[1,0]
	v_pk_mul_f32 v[38:39], v[42:43], v[38:39] op_sel:[1,0]
	v_pk_fma_f32 v[40:41], v[8:9], v[40:41], v[12:13]
	v_pk_fma_f32 v[38:39], v[6:7], v[38:39], v[10:11]
	v_cndmask_b32_e64 v41, v250, v41, s[8:9]
	v_cndmask_b32_e64 v40, v250, v40, s[8:9]
	v_cndmask_b32_e64 v39, v250, v39, s[8:9]
	v_cndmask_b32_e64 v38, v250, v38, s[8:9]
	s_cbranch_vccz .LBB0_574
	s_andn2_b64 vcc, exec, s[10:11]
	s_cbranch_vccz .LBB0_575

.LBB0_484:
	v_mov_b64_e32 v[38:39], v[222:223]
	s_and_b64 vcc, exec, s[4:5]
	s_mov_b64 s[10:11], -1
	s_waitcnt lgkmcnt(0)
	v_sub_f32_e32 v31, v31, v38
	v_sub_f32_e32 v30, v30, v38
	v_sub_f32_e32 v33, v33, v38
	v_sub_f32_e32 v32, v32, v38
	v_pk_mul_f32 v[32:33], v[38:39], v[32:33] op_sel:[1,0]
	v_pk_mul_f32 v[30:31], v[38:39], v[30:31] op_sel:[1,0]
	v_pk_fma_f32 v[32:33], v[8:9], v[32:33], v[12:13]
	v_pk_fma_f32 v[30:31], v[6:7], v[30:31], v[10:11]
	v_cndmask_b32_e64 v33, v250, v33, s[8:9]
	v_cndmask_b32_e64 v32, v250, v32, s[8:9]
	v_cndmask_b32_e64 v31, v250, v31, s[8:9]
	v_cndmask_b32_e64 v30, v250, v30, s[8:9]
	s_cbranch_vccz .LBB0_576
	s_andn2_b64 vcc, exec, s[10:11]
	s_cbranch_vccz .LBB0_577

.LBB0_488:
	v_mov_b64_e32 v[30:31], v[224:225]
	s_and_b64 vcc, exec, s[4:5]
	s_mov_b64 s[10:11], -1
	s_waitcnt lgkmcnt(0)
	v_sub_f32_e32 v33, v35, v30
	v_sub_f32_e32 v32, v34, v30
	v_sub_f32_e32 v35, v37, v30
	v_sub_f32_e32 v34, v36, v30
	v_pk_mul_f32 v[34:35], v[30:31], v[34:35] op_sel:[1,0]
	v_pk_mul_f32 v[30:31], v[30:31], v[32:33] op_sel:[1,0]
	v_pk_fma_f32 v[32:33], v[8:9], v[34:35], v[12:13]
	v_pk_fma_f32 v[30:31], v[6:7], v[30:31], v[10:11]
	v_cndmask_b32_e64 v33, v250, v33, s[8:9]
	v_cndmask_b32_e64 v32, v250, v32, s[8:9]
	v_cndmask_b32_e64 v31, v250, v31, s[8:9]
	v_cndmask_b32_e64 v30, v250, v30, s[8:9]
	s_cbranch_vccz .LBB0_578
	s_andn2_b64 vcc, exec, s[10:11]
	s_cbranch_vccz .LBB0_579

.LBB0_492:
	v_mov_b64_e32 v[30:31], v[226:227]
	s_and_b64 vcc, exec, s[4:5]
	s_mov_b64 s[10:11], -1
	s_waitcnt lgkmcnt(0)
	v_sub_f32_e32 v27, v27, v30
	v_sub_f32_e32 v26, v26, v30
	v_sub_f32_e32 v29, v29, v30
	v_sub_f32_e32 v28, v28, v30
	v_pk_mul_f32 v[28:29], v[30:31], v[28:29] op_sel:[1,0]
	v_pk_mul_f32 v[26:27], v[30:31], v[26:27] op_sel:[1,0]
	v_pk_fma_f32 v[28:29], v[8:9], v[28:29], v[12:13]
	v_pk_fma_f32 v[26:27], v[6:7], v[26:27], v[10:11]
	v_cndmask_b32_e64 v29, v250, v29, s[8:9]
	v_cndmask_b32_e64 v28, v250, v28, s[8:9]
	v_cndmask_b32_e64 v27, v250, v27, s[8:9]
	v_cndmask_b32_e64 v26, v250, v26, s[8:9]
	s_cbranch_vccz .LBB0_580
	s_andn2_b64 vcc, exec, s[10:11]
	s_cbranch_vccz .LBB0_581

.LBB0_496:
	v_mov_b64_e32 v[26:27], v[228:229]
	s_and_b64 vcc, exec, s[4:5]
	s_mov_b64 s[10:11], -1
	s_waitcnt lgkmcnt(0)
	v_sub_f32_e32 v23, v23, v26
	v_sub_f32_e32 v22, v22, v26
	v_sub_f32_e32 v25, v25, v26
	v_sub_f32_e32 v24, v24, v26
	v_pk_mul_f32 v[24:25], v[26:27], v[24:25] op_sel:[1,0]
	v_pk_mul_f32 v[22:23], v[26:27], v[22:23] op_sel:[1,0]
	v_pk_fma_f32 v[24:25], v[8:9], v[24:25], v[12:13]
	v_pk_fma_f32 v[22:23], v[6:7], v[22:23], v[10:11]
	v_cndmask_b32_e64 v25, v250, v25, s[8:9]
	v_cndmask_b32_e64 v24, v250, v24, s[8:9]
	v_cndmask_b32_e64 v23, v250, v23, s[8:9]
	v_cndmask_b32_e64 v22, v250, v22, s[8:9]
	s_cbranch_vccz .LBB0_582
	s_andn2_b64 vcc, exec, s[10:11]
	s_cbranch_vccz .LBB0_583

.LBB0_500:
	v_mov_b64_e32 v[22:23], v[230:231]
	s_and_b64 vcc, exec, s[4:5]
	s_mov_b64 s[10:11], -1
	s_waitcnt lgkmcnt(0)
	v_sub_f32_e32 v19, v19, v22
	v_sub_f32_e32 v18, v18, v22
	v_sub_f32_e32 v21, v21, v22
	v_sub_f32_e32 v20, v20, v22
	v_pk_mul_f32 v[20:21], v[22:23], v[20:21] op_sel:[1,0]
	v_pk_mul_f32 v[18:19], v[22:23], v[18:19] op_sel:[1,0]
	v_pk_fma_f32 v[20:21], v[8:9], v[20:21], v[12:13]
	v_pk_fma_f32 v[18:19], v[6:7], v[18:19], v[10:11]
	v_cndmask_b32_e64 v21, v250, v21, s[8:9]
	v_cndmask_b32_e64 v20, v250, v20, s[8:9]
	v_cndmask_b32_e64 v19, v250, v19, s[8:9]
	v_cndmask_b32_e64 v18, v250, v18, s[8:9]
	s_cbranch_vccz .LBB0_584
	s_andn2_b64 vcc, exec, s[10:11]
	s_cbranch_vccz .LBB0_585

.LBB0_504:
	v_mov_b64_e32 v[18:19], v[232:233]
	s_and_b64 vcc, exec, s[4:5]
	s_mov_b64 s[10:11], -1
	s_waitcnt lgkmcnt(0)
	v_sub_f32_e32 v15, v15, v18
	v_sub_f32_e32 v14, v14, v18
	v_sub_f32_e32 v17, v17, v18
	v_sub_f32_e32 v16, v16, v18
	v_pk_mul_f32 v[16:17], v[18:19], v[16:17] op_sel:[1,0]
	v_pk_mul_f32 v[14:15], v[18:19], v[14:15] op_sel:[1,0]
	v_pk_fma_f32 v[16:17], v[8:9], v[16:17], v[12:13]
	v_pk_fma_f32 v[14:15], v[6:7], v[14:15], v[10:11]
	v_cndmask_b32_e64 v17, v250, v17, s[8:9]
	v_cndmask_b32_e64 v16, v250, v16, s[8:9]
	v_cndmask_b32_e64 v15, v250, v15, s[8:9]
	v_cndmask_b32_e64 v14, v250, v14, s[8:9]
	s_cbranch_vccz .LBB0_586
	s_andn2_b64 vcc, exec, s[10:11]
	s_cbranch_vccz .LBB0_587

.LBB0_508:
	v_mov_b64_e32 v[14:15], v[234:235]
	s_and_b64 vcc, exec, s[4:5]
	s_mov_b64 s[4:5], -1
	s_waitcnt lgkmcnt(0)
	v_sub_f32_e32 v3, v3, v14
	v_sub_f32_e32 v2, v2, v14
	v_sub_f32_e32 v5, v5, v14
	v_sub_f32_e32 v4, v4, v14
	v_pk_mul_f32 v[4:5], v[14:15], v[4:5] op_sel:[1,0]
	v_pk_mul_f32 v[2:3], v[14:15], v[2:3] op_sel:[1,0]
	v_pk_fma_f32 v[4:5], v[8:9], v[4:5], v[12:13]
	v_pk_fma_f32 v[2:3], v[6:7], v[2:3], v[10:11]
	v_cndmask_b32_e64 v5, v250, v5, s[8:9]
	v_cndmask_b32_e64 v4, v250, v4, s[8:9]
	v_cndmask_b32_e64 v3, v250, v3, s[8:9]
	v_cndmask_b32_e64 v2, v250, v2, s[8:9]
	s_cbranch_vccz .LBB0_588
	s_andn2_b64 vcc, exec, s[4:5]
	s_cbranch_vccz .LBB0_589
